# lever 1: chunk-prep top-of-task and S1 vmcnt waits (meant for the first task's loads) no longer wait for the previous task's stores
# speedup vs baseline: 1.0037x; 1.0037x over previous
.LBB0_355:
	s_or_b64 exec, exec, s[14:15]
	s_waitcnt vmcnt(23)
	v_cndmask_b32_e64 v40, 0, v40, s[2:3]
	v_cndmask_b32_e64 v41, 0, v41, s[2:3]
	v_cndmask_b32_e64 v50, 0, v42, s[2:3]
	v_cndmask_b32_e64 v43, 0, v43, s[2:3]
	s_waitcnt vmcnt(21)
	v_cndmask_b32_e64 v42, 0, v94, s[4:5]
	v_cndmask_b32_e64 v49, 0, v95, s[4:5]
	v_cndmask_b32_e64 v56, 0, v96, s[4:5]
	v_cndmask_b32_e64 v51, 0, v97, s[4:5]
	s_waitcnt vmcnt(19)
	v_cndmask_b32_e64 v48, v62, 0, s[6:7]
	v_cndmask_b32_e64 v57, v63, 0, s[6:7]
	v_cndmask_b32_e64 v64, v64, 0, s[6:7]
	v_cndmask_b32_e64 v63, v65, 0, s[6:7]
	v_cndmask_b32_e64 v62, 0, v80, s[2:3]
	v_cndmask_b32_e64 v65, 0, v81, s[2:3]
	v_cndmask_b32_e64 v80, 0, v82, s[2:3]
	v_cndmask_b32_e64 v71, 0, v83, s[2:3]
	v_cndmask_b32_e64 v70, 0, v76, s[4:5]
	v_cndmask_b32_e64 v77, 0, v77, s[4:5]
	v_cndmask_b32_e64 v84, 0, v78, s[4:5]
	v_cndmask_b32_e64 v79, 0, v79, s[4:5]
	s_waitcnt vmcnt(18)
	v_cndmask_b32_e64 v76, v86, 0, s[6:7]
	v_cndmask_b32_e64 v81, v87, 0, s[6:7]
	v_cndmask_b32_e64 v88, v88, 0, s[6:7]
	v_cndmask_b32_e64 v83, v89, 0, s[6:7]
	s_waitcnt vmcnt(8)
	v_cndmask_b32_e64 v78, 0, v90, s[2:3]
	v_cndmask_b32_e64 v85, 0, v91, s[2:3]
	v_cndmask_b32_e64 v90, 0, v92, s[2:3]
	v_cndmask_b32_e64 v87, 0, v93, s[2:3]
	s_waitcnt vmcnt(7)
	v_cndmask_b32_e64 v82, 0, v102, s[4:5]
	v_cndmask_b32_e64 v89, 0, v103, s[4:5]
	v_cndmask_b32_e64 v92, 0, v104, s[4:5]
	v_cndmask_b32_e64 v91, 0, v105, s[4:5]
	s_waitcnt vmcnt(0)
	v_cndmask_b32_e64 v86, v98, 0, s[6:7]
	v_cndmask_b32_e64 v93, v99, 0, s[6:7]
	v_cndmask_b32_e64 v94, v100, 0, s[6:7]
	v_cndmask_b32_e64 v95, v101, 0, s[6:7]
	s_andn2_b64 vcc, exec, s[10:11]
	s_cbranch_vccz .LBB0_357
	s_branch .LBB0_523

.LBB0_363:
	s_waitcnt lgkmcnt(0)
	s_barrier
	v_cmp_gt_i32_e64 s[2:3], 64, v132
	v_lshl_add_u32 v96, v132, 2, 0
	s_and_saveexec_b64 s[6:7], s[2:3]
	s_cbranch_execz .LBB0_365
	v_add_u32_e32 v97, 0x1f700, v96
	v_add_u32_e32 v98, 0x1f800, v96
	s_nop 0
	ds_write_b32 v97, v129
	s_nop 0
	ds_write_b32 v98, v135

.LBB0_370:
	s_or_b64 exec, exec, s[6:7]
	s_lshl_b32 s6, s24, 6
	s_ashr_i32 s5, s4, 31
	s_and_b32 s25, s6, 0x7c0
	s_lshl_b64 s[4:5], s[4:5], 18
	s_lshl_b32 s6, s25, 7
	s_or_b32 s4, s4, s6
	s_add_i32 s65, s24, s88
	s_cmpk_gt_i32 s65, 0x7ff
	s_cselect_b64 s[26:27], -1, 0
	s_cmpk_lt_i32 s65, 0x800
	v_and_b32_e32 v142, 15, v132
	v_ashrrev_i32_e32 v128, 4, v132
	s_cselect_b32 s31, s65, -1
	s_add_i32 s7, 0, 0x1f700
	v_lshlrev_b32_e32 v112, 2, v128
	v_lshl_add_u32 v97, v142, 5, 0
	s_waitcnt lgkmcnt(0)
	s_barrier
	v_add_u32_e32 v105, s7, v112
	v_add_u32_e32 v124, 0x20400, v97
	ds_read_b32 v96, v105
	ds_read_b128 v[100:103], v124 offset:1552
	ds_read_b128 v[108:111], v124 offset:16
	ds_read_b128 v[114:117], v124 offset:528
	ds_read_b128 v[118:121], v124 offset:1040
	v_lshlrev_b32_e32 v136, 16, v43
	v_and_b32_e32 v137, 0xffff0000, v43
	v_lshlrev_b32_e32 v126, 16, v51
	v_and_b32_e32 v127, 0xffff0000, v51
	s_waitcnt lgkmcnt(2)
	v_pk_fma_f32 v[136:137], v[110:111], v[136:137], 0 op_sel_hi:[1,1,0]
	v_lshlrev_b32_e32 v138, 16, v50
	v_and_b32_e32 v139, 0xffff0000, v50
	v_lshlrev_b32_e32 v122, 16, v63
	v_and_b32_e32 v123, 0xffff0000, v63
	v_pk_fma_f32 v[138:139], v[108:109], v[138:139], 0 op_sel_hi:[1,1,0]
	v_lshlrev_b32_e32 v146, 16, v3
	v_and_b32_e32 v147, 0xffff0000, v3
	s_waitcnt lgkmcnt(1)
	v_pk_fma_f32 v[126:127], v[116:117], v[126:127], v[136:137]
	v_lshlrev_b32_e32 v136, 16, v56
	v_and_b32_e32 v137, 0xffff0000, v56
	v_pk_fma_f32 v[146:147], v[110:111], v[146:147], 0 op_sel_hi:[1,1,0]
	v_lshlrev_b32_e32 v110, 16, v2
	v_and_b32_e32 v111, 0xffff0000, v2
	v_pk_fma_f32 v[136:137], v[114:115], v[136:137], v[138:139]
	v_lshlrev_b32_e32 v138, 16, v7
	v_and_b32_e32 v139, 0xffff0000, v7
	s_waitcnt lgkmcnt(0)
	v_pk_fma_f32 v[122:123], v[120:121], v[122:123], v[126:127]
	v_lshlrev_b32_e32 v126, 16, v64
	v_and_b32_e32 v127, 0xffff0000, v64
	v_pk_fma_f32 v[148:149], v[108:109], v[110:111], 0 op_sel_hi:[1,1,0]
	v_pk_fma_f32 v[138:139], v[116:117], v[138:139], v[146:147]
	v_lshlrev_b32_e32 v116, 16, v6
	v_and_b32_e32 v117, 0xffff0000, v6
	v_pk_fma_f32 v[126:127], v[118:119], v[126:127], v[136:137]
	v_lshlrev_b32_e32 v136, 16, v11
	v_and_b32_e32 v137, 0xffff0000, v11
	v_mov_b32_e32 v107, s23
	v_mul_f32_e32 v96, 0x3fb8aa3b, v96
	v_pk_fma_f32 v[146:147], v[114:115], v[116:117], v[148:149]
	v_pk_fma_f32 v[136:137], v[120:121], v[136:137], v[138:139]
	v_lshlrev_b32_e32 v120, 16, v10
	v_and_b32_e32 v121, 0xffff0000, v10
	v_exp_f32_e32 v106, v96
	ds_read_b128 v[96:99], v124 offset:512
	ds_read_b128 v[108:111], v124 offset:1024
	ds_read_b128 v[114:117], v124 offset:1536
	v_pk_fma_f32 v[138:139], v[118:119], v[120:121], v[146:147]
	ds_read_b32 v141, v107
	ds_read_b128 v[118:121], v124
	s_nop 0
	v_lshlrev_b32_e32 v146, 16, v19
	v_and_b32_e32 v147, 0xffff0000, v19
	v_lshlrev_b32_e32 v148, 16, v15
	v_and_b32_e32 v149, 0xffff0000, v15
	v_pk_fma_f32 v[122:123], v[102:103], v[146:147], v[122:123]
	v_lshlrev_b32_e32 v146, 16, v18
	v_and_b32_e32 v147, 0xffff0000, v18
	v_pk_fma_f32 v[102:103], v[102:103], v[148:149], v[136:137]
	v_lshlrev_b32_e32 v136, 16, v14
	v_and_b32_e32 v137, 0xffff0000, v14
	v_pk_fma_f32 v[126:127], v[100:101], v[146:147], v[126:127]
	v_pk_fma_f32 v[136:137], v[100:101], v[136:137], v[138:139]
	v_lshlrev_b32_e32 v100, 16, v40
	v_and_b32_e32 v101, 0xffff0000, v40
	v_lshlrev_b32_e32 v146, 16, v41
	v_and_b32_e32 v147, 0xffff0000, v41
	s_waitcnt lgkmcnt(0)
	v_pk_fma_f32 v[138:139], v[118:119], v[100:101], 0 op_sel_hi:[1,1,0]
	v_lshlrev_b32_e32 v100, 16, v1
	v_and_b32_e32 v101, 0xffff0000, v1
	v_pk_fma_f32 v[146:147], v[120:121], v[146:147], 0 op_sel_hi:[1,1,0]
	v_pk_fma_f32 v[120:121], v[120:121], v[100:101], 0 op_sel_hi:[1,1,0]
	v_lshlrev_b32_e32 v100, 16, v0
	v_and_b32_e32 v101, 0xffff0000, v0
	v_pk_fma_f32 v[118:119], v[118:119], v[100:101], 0 op_sel_hi:[1,1,0]
	v_mul_f32_e32 v100, 0xbfb8aa3b, v122
	v_exp_f32_e32 v100, v100
	v_mul_f32_e32 v101, 0xbfb8aa3b, v123
	v_exp_f32_e32 v101, v101
	v_and_b32_e32 v125, 64, v140
	v_add_f32_e32 v100, 1.0, v100
	v_rcp_f32_e32 v148, v100
	v_add_f32_e32 v100, 1.0, v101
	v_rcp_f32_e32 v149, v100
	v_xor_b32_e32 v113, 1, v140
	v_add_u32_e32 v107, 64, v125
	v_cmp_lt_i32_e32 vcc, v113, v107
	v_pk_mul_f32 v[122:123], v[122:123], v[148:149]
	v_lshlrev_b32_e32 v148, 16, v49
	v_and_b32_e32 v149, 0xffff0000, v49
	v_pk_fma_f32 v[146:147], v[98:99], v[148:149], v[146:147]
	v_lshlrev_b32_e32 v148, 16, v42
	v_and_b32_e32 v149, 0xffff0000, v42
	v_pk_fma_f32 v[138:139], v[96:97], v[148:149], v[138:139]
	v_lshlrev_b32_e32 v148, 16, v5
	v_and_b32_e32 v149, 0xffff0000, v5
	v_cndmask_b32_e32 v100, v140, v113, vcc
	v_mul_f32_e32 v113, 0xbfb8aa3b, v126
	v_pk_fma_f32 v[98:99], v[98:99], v[148:149], v[120:121]
	v_lshlrev_b32_e32 v120, 16, v4
	v_and_b32_e32 v121, 0xffff0000, v4
	v_exp_f32_e32 v113, v113
	v_pk_fma_f32 v[96:97], v[96:97], v[120:121], v[118:119]
	v_mul_f32_e32 v118, 0xbfb8aa3b, v127
	v_exp_f32_e32 v121, v118
	v_lshlrev_b32_e32 v148, 16, v57
	v_and_b32_e32 v149, 0xffff0000, v57
	v_pk_fma_f32 v[146:147], v[110:111], v[148:149], v[146:147]
	v_lshlrev_b32_e32 v148, 16, v17
	v_and_b32_e32 v149, 0xffff0000, v17
	v_pk_fma_f32 v[146:147], v[116:117], v[148:149], v[146:147]
	v_lshlrev_b32_e32 v148, 16, v48
	v_and_b32_e32 v149, 0xffff0000, v48
	v_add_f32_e32 v113, 1.0, v113
	v_pk_fma_f32 v[138:139], v[108:109], v[148:149], v[138:139]
	v_lshlrev_b32_e32 v148, 16, v16
	v_and_b32_e32 v149, 0xffff0000, v16
	v_rcp_f32_e32 v120, v113
	v_add_f32_e32 v113, 1.0, v121
	v_pk_fma_f32 v[138:139], v[114:115], v[148:149], v[138:139]
	v_lshlrev_b32_e32 v148, 16, v9
	v_and_b32_e32 v149, 0xffff0000, v9
	v_rcp_f32_e32 v121, v113
	v_mul_f32_e32 v113, 0xbfb8aa3b, v146
	v_pk_fma_f32 v[98:99], v[110:111], v[148:149], v[98:99]
	v_lshlrev_b32_e32 v110, 16, v8
	v_and_b32_e32 v111, 0xffff0000, v8
	v_exp_f32_e32 v113, v113
	v_mul_f32_e32 v125, 0xbfb8aa3b, v147
	v_pk_fma_f32 v[96:97], v[108:109], v[110:111], v[96:97]
	v_mul_f32_e32 v108, 0xbfb8aa3b, v138
	v_mul_f32_e32 v109, 0xbfb8aa3b, v139
	v_exp_f32_e32 v125, v125
	v_exp_f32_e32 v108, v108
	v_exp_f32_e32 v109, v109
	v_add_f32_e32 v113, 1.0, v113
	v_pk_mul_f32 v[120:121], v[126:127], v[120:121]
	v_rcp_f32_e32 v126, v113
	v_add_f32_e32 v113, 1.0, v125
	v_add_f32_e32 v108, 1.0, v108
	v_add_f32_e32 v109, 1.0, v109
	v_rcp_f32_e32 v127, v113
	v_rcp_f32_e32 v108, v108
	v_rcp_f32_e32 v109, v109
	v_mul_f32_e32 v113, 0xbfb8aa3b, v102
	v_exp_f32_e32 v113, v113
	v_mul_f32_e32 v125, 0xbfb8aa3b, v103
	v_exp_f32_e32 v125, v125
	v_pk_mul_f32 v[108:109], v[138:139], v[108:109]
	v_lshlrev_b32_e32 v138, 16, v13
	v_and_b32_e32 v139, 0xffff0000, v13
	v_pk_fma_f32 v[98:99], v[116:117], v[138:139], v[98:99]
	v_lshlrev_b32_e32 v116, 16, v12
	v_and_b32_e32 v117, 0xffff0000, v12
	v_add_f32_e32 v113, 1.0, v113
	v_pk_fma_f32 v[96:97], v[114:115], v[116:117], v[96:97]
	v_rcp_f32_e32 v116, v113
	v_add_f32_e32 v113, 1.0, v125
	v_rcp_f32_e32 v117, v113
	v_mul_f32_e32 v113, 0xbfb8aa3b, v136
	v_exp_f32_e32 v113, v113
	v_mul_f32_e32 v125, 0xbfb8aa3b, v137
	v_exp_f32_e32 v125, v125
	v_pk_mul_f32 v[102:103], v[102:103], v[116:117]
	v_add_f32_e32 v113, 1.0, v113
	v_mul_f32_e32 v117, 0xbfb8aa3b, v98
	v_rcp_f32_e32 v116, v113
	v_add_f32_e32 v113, 1.0, v125
	v_exp_f32_e32 v125, v117
	v_mul_f32_e32 v117, 0xbfb8aa3b, v99
	v_exp_f32_e32 v130, v117
	v_rcp_f32_e32 v117, v113
	v_add_f32_e32 v113, 1.0, v125
	v_mul_f32_e32 v125, 0xbfb8aa3b, v96
	v_rcp_f32_e32 v138, v113
	v_add_f32_e32 v113, 1.0, v130
	v_exp_f32_e32 v125, v125
	v_mul_f32_e32 v130, 0xbfb8aa3b, v97
	v_exp_f32_e32 v130, v130
	v_rcp_f32_e32 v139, v113
	v_add_f32_e32 v113, 1.0, v125
	v_rcp_f32_e32 v148, v113
	v_add_f32_e32 v113, 1.0, v130
	v_rcp_f32_e32 v149, v113
	v_pk_mul_f32 v[126:127], v[146:147], v[126:127]
	v_pk_mul_f32 v[114:115], v[108:109], v[108:109]
	v_pk_mul_f32 v[150:151], v[98:99], v[138:139]
	v_pk_mul_f32 v[148:149], v[96:97], v[148:149]
	v_pk_mul_f32 v[146:147], v[126:127], v[126:127]
	v_pk_mul_f32 v[96:97], v[148:149], v[148:149]
	v_mov_b32_e32 v99, v114
	v_mov_b32_e32 v98, v96
	v_mov_b32_e32 v114, v97
	v_pk_mul_f32 v[96:97], v[150:151], v[150:151]
	v_pk_mul_f32 v[136:137], v[136:137], v[116:117]
	v_pk_add_f32 v[98:99], v[98:99], v[114:115]
	v_mov_b32_e32 v114, v96
	v_mov_b32_e32 v115, v146
	v_pk_mul_f32 v[110:111], v[120:121], v[120:121]
	v_pk_add_f32 v[98:99], v[98:99], v[114:115]
	v_pk_mul_f32 v[114:115], v[136:137], v[136:137]
	v_mov_b32_e32 v146, v97
	v_pk_add_f32 v[96:97], v[98:99], v[146:147]
	v_mov_b32_e32 v98, v114
	v_mov_b32_e32 v99, v110
	v_pk_mul_f32 v[118:119], v[122:123], v[122:123]
	v_pk_mul_f32 v[116:117], v[102:103], v[102:103]
	v_pk_add_f32 v[96:97], v[96:97], v[98:99]
	v_mov_b32_e32 v110, v115
	v_pk_add_f32 v[96:97], v[96:97], v[110:111]
	v_mov_b32_e32 v98, v116
	v_mov_b32_e32 v99, v118
	v_pk_add_f32 v[96:97], v[96:97], v[98:99]
	v_mov_b32_e32 v118, v117
	v_lshlrev_b32_e32 v101, 2, v100
	v_pk_add_f32 v[96:97], v[96:97], v[118:119]
	ds_bpermute_b32 v99, v101, v97
	ds_bpermute_b32 v98, v101, v96
	v_xor_b32_e32 v100, 2, v140
	v_cmp_lt_i32_e32 vcc, v100, v107
	v_lshl_add_u32 v104, v142, 4, 0
	v_mad_u64_u32 v[138:139], s[8:9], v128, s33, v[104:105]
	v_cndmask_b32_e32 v100, v140, v100, vcc
	v_lshlrev_b32_e32 v113, 2, v100
	s_waitcnt lgkmcnt(0)
	v_pk_add_f32 v[96:97], v[96:97], v[98:99]
	ds_bpermute_b32 v99, v113, v97
	ds_bpermute_b32 v98, v113, v96
	v_xor_b32_e32 v100, 4, v140
	v_cmp_lt_i32_e32 vcc, v100, v107
	s_add_i32 s6, 0, 0x1f800
	s_lshl_b64 s[28:29], s[4:5], 1
	v_cndmask_b32_e32 v100, v140, v100, vcc
	v_lshlrev_b32_e32 v115, 2, v100
	s_waitcnt lgkmcnt(0)
	v_pk_add_f32 v[96:97], v[96:97], v[98:99]
	ds_bpermute_b32 v99, v115, v97
	ds_bpermute_b32 v98, v115, v96
	v_xor_b32_e32 v100, 8, v140
	v_cmp_lt_i32_e32 vcc, v100, v107
	s_add_u32 s4, s42, s28
	s_addc_u32 s5, s43, s29
	v_cndmask_b32_e32 v100, v140, v100, vcc
	v_lshlrev_b32_e32 v116, 2, v100
	s_waitcnt lgkmcnt(0)
	v_pk_add_f32 v[96:97], v[96:97], v[98:99]
	ds_bpermute_b32 v99, v116, v97
	ds_bpermute_b32 v98, v116, v96
	v_add_u32_e32 v100, 0x200, v132
	v_ashrrev_i32_e32 v134, 4, v100
	v_lshlrev_b32_e32 v117, 2, v134
	v_add_u32_e32 v114, s7, v117
	s_waitcnt lgkmcnt(0)
	v_pk_add_f32 v[96:97], v[96:97], v[98:99]
	v_ashrrev_i32_e32 v133, 31, v132
	v_pk_add_f32 v[110:111], v[96:97], s[22:23] op_sel_hi:[1,0]
	v_lshl_add_u64 v[146:147], v[132:133], 4, s[4:5]
	v_mul_f32_e32 v96, 0x4b800000, v111
	v_cmp_gt_f32_e32 vcc, s36, v111
	v_lshlrev_b32_e32 v154, 16, v79
	v_and_b32_e32 v155, 0xffff0000, v79
	v_cndmask_b32_e32 v96, v111, v96, vcc
	v_rsq_f32_e32 v96, v96
	v_lshlrev_b32_e32 v160, 16, v83
	v_and_b32_e32 v161, 0xffff0000, v83
	v_lshlrev_b32_e32 v168, 16, v23
	v_mul_f32_e32 v97, 0x45800000, v96
	v_cndmask_b32_e32 v96, v96, v97, vcc
	v_mul_f32_e32 v96, 0x3db504f3, v96
	v_pk_mul_f32 v[108:109], v[108:109], v[96:97] op_sel_hi:[1,0]
	v_pk_mul_f32 v[126:127], v[126:127], v[96:97] op_sel_hi:[1,0]
	v_pk_mul_f32 v[120:121], v[120:121], v[96:97] op_sel_hi:[1,0]
	v_pk_mul_f32 v[122:123], v[122:123], v[96:97] op_sel_hi:[1,0]
	v_cvt_pk_bf16_f32 v96, v108, v109
	v_cvt_pk_bf16_f32 v97, v126, v127
	v_cvt_pk_bf16_f32 v98, v120, v121
	v_cvt_pk_bf16_f32 v99, v122, v123
	ds_write_b128 v138, v[96:99]
	v_mul_f32_e32 v98, 0x4b800000, v110
	v_cmp_gt_f32_e32 vcc, s36, v110
	v_pk_mul_f32 v[96:97], v[106:107], v[108:109] op_sel_hi:[0,1]
	v_cvt_pk_bf16_f32 v118, v96, v97
	v_cndmask_b32_e32 v98, v110, v98, vcc
	v_rsq_f32_e32 v98, v98
	v_pk_mul_f32 v[96:97], v[106:107], v[126:127] op_sel_hi:[0,1]
	v_cvt_pk_bf16_f32 v119, v96, v97
	v_pk_mul_f32 v[96:97], v[106:107], v[120:121] op_sel_hi:[0,1]
	v_cvt_pk_bf16_f32 v120, v96, v97
	v_mul_f32_e32 v96, 0x45800000, v98
	v_cndmask_b32_e32 v96, v98, v96, vcc
	v_mul_f32_e32 v96, 0x3db504f3, v96
	v_pk_mul_f32 v[122:123], v[106:107], v[122:123] op_sel_hi:[0,1]
	v_pk_mul_f32 v[108:109], v[148:149], v[96:97] op_sel_hi:[1,0]
	v_pk_mul_f32 v[110:111], v[150:151], v[96:97] op_sel_hi:[1,0]
	v_pk_mul_f32 v[106:107], v[136:137], v[96:97] op_sel_hi:[1,0]
	v_pk_mul_f32 v[102:103], v[102:103], v[96:97] op_sel_hi:[1,0]
	v_cvt_pk_bf16_f32 v96, v108, v109
	v_cvt_pk_bf16_f32 v97, v110, v111
	v_cvt_pk_bf16_f32 v98, v106, v107
	v_cvt_pk_bf16_f32 v99, v102, v103
	v_mad_u64_u32 v[136:137], s[8:9], v134, s33, v[104:105]
	ds_read_b32 v125, v114
	ds_write_b128 v136, v[96:99]
	ds_read_b128 v[96:99], v124 offset:2064
	v_cvt_pk_bf16_f32 v121, v122, v123
	global_store_dwordx4 v[146:147], v[118:121], off
	v_lshlrev_b32_e32 v122, 16, v71
	v_and_b32_e32 v123, 0xffff0000, v71
	v_lshlrev_b32_e32 v146, 16, v27
	v_and_b32_e32 v147, 0xffff0000, v27
	ds_read_b128 v[118:121], v124 offset:2048
	s_waitcnt lgkmcnt(1)
	v_pk_fma_f32 v[122:123], v[98:99], v[122:123], 0 op_sel_hi:[1,1,0]
	v_lshlrev_b32_e32 v126, 16, v80
	v_and_b32_e32 v127, 0xffff0000, v80
	v_pk_fma_f32 v[150:151], v[98:99], v[146:147], 0 op_sel_hi:[1,1,0]
	v_lshlrev_b32_e32 v98, 16, v26
	v_and_b32_e32 v99, 0xffff0000, v26
	v_pk_fma_f32 v[126:127], v[96:97], v[126:127], 0 op_sel_hi:[1,1,0]
	v_pk_fma_f32 v[152:153], v[96:97], v[98:99], 0 op_sel_hi:[1,1,0]
	ds_read_b128 v[96:99], v124 offset:2576
	ds_read_b128 v[146:149], v124 offset:2560
	v_and_b32_e32 v169, 0xffff0000, v23
	v_add_u32_e32 v130, s6, v112
	v_add_u32_e32 v137, s6, v117
	s_waitcnt lgkmcnt(1)
	v_pk_fma_f32 v[122:123], v[98:99], v[154:155], v[122:123]
	v_lshlrev_b32_e32 v154, 16, v84
	v_and_b32_e32 v155, 0xffff0000, v84
	v_pk_fma_f32 v[126:127], v[96:97], v[154:155], v[126:127]
	v_lshlrev_b32_e32 v154, 16, v31
	v_and_b32_e32 v155, 0xffff0000, v31
	v_pk_fma_f32 v[154:155], v[98:99], v[154:155], v[150:151]
	v_lshlrev_b32_e32 v98, 16, v30
	v_and_b32_e32 v99, 0xffff0000, v30
	v_pk_fma_f32 v[158:159], v[96:97], v[98:99], v[152:153]
	ds_read_b128 v[96:99], v124 offset:3088
	ds_read_b128 v[150:153], v124 offset:3072
	s_cmp_lt_i32 s31, 0
	s_waitcnt lgkmcnt(1)
	v_pk_fma_f32 v[122:123], v[98:99], v[160:161], v[122:123]
	v_lshlrev_b32_e32 v160, 16, v88
	v_and_b32_e32 v161, 0xffff0000, v88
	v_pk_fma_f32 v[126:127], v[96:97], v[160:161], v[126:127]
	v_lshlrev_b32_e32 v160, 16, v35
	v_and_b32_e32 v161, 0xffff0000, v35
	v_pk_fma_f32 v[154:155], v[98:99], v[160:161], v[154:155]
	v_lshlrev_b32_e32 v98, 16, v34
	v_and_b32_e32 v99, 0xffff0000, v34
	v_pk_fma_f32 v[162:163], v[96:97], v[98:99], v[158:159]
	ds_read_b128 v[96:99], v124 offset:3600
	ds_read_b128 v[158:161], v124 offset:3584
	ds_read_b32 v112, v105
	s_waitcnt lgkmcnt(2)
	v_pk_fma_f32 v[122:123], v[98:99], v[168:169], v[122:123]
	v_lshlrev_b32_e32 v168, 16, v22
	v_and_b32_e32 v169, 0xffff0000, v22
	v_pk_fma_f32 v[126:127], v[96:97], v[168:169], v[126:127]
	v_lshlrev_b32_e32 v168, 16, v39
	v_and_b32_e32 v169, 0xffff0000, v39
	v_pk_fma_f32 v[154:155], v[98:99], v[168:169], v[154:155]
	v_lshlrev_b32_e32 v98, 16, v38
	v_and_b32_e32 v99, 0xffff0000, v38
	v_pk_fma_f32 v[162:163], v[96:97], v[98:99], v[162:163]
	v_lshlrev_b32_e32 v96, 16, v65
	v_and_b32_e32 v97, 0xffff0000, v65
	v_lshlrev_b32_e32 v168, 16, v25
	v_and_b32_e32 v169, 0xffff0000, v25
	v_pk_fma_f32 v[96:97], v[120:121], v[96:97], 0 op_sel_hi:[1,1,0]
	v_lshlrev_b32_e32 v98, 16, v62
	v_and_b32_e32 v99, 0xffff0000, v62
	v_pk_fma_f32 v[120:121], v[120:121], v[168:169], 0 op_sel_hi:[1,1,0]
	v_lshlrev_b32_e32 v168, 16, v24
	v_and_b32_e32 v169, 0xffff0000, v24
	v_pk_fma_f32 v[98:99], v[118:119], v[98:99], 0 op_sel_hi:[1,1,0]
	v_pk_fma_f32 v[118:119], v[118:119], v[168:169], 0 op_sel_hi:[1,1,0]
	v_lshlrev_b32_e32 v168, 16, v77
	v_and_b32_e32 v169, 0xffff0000, v77
	v_pk_fma_f32 v[96:97], v[148:149], v[168:169], v[96:97]
	v_lshlrev_b32_e32 v168, 16, v70
	v_and_b32_e32 v169, 0xffff0000, v70
	v_pk_fma_f32 v[98:99], v[146:147], v[168:169], v[98:99]
	v_lshlrev_b32_e32 v168, 16, v29
	v_and_b32_e32 v169, 0xffff0000, v29
	v_pk_fma_f32 v[120:121], v[148:149], v[168:169], v[120:121]
	v_lshlrev_b32_e32 v148, 16, v28
	v_and_b32_e32 v149, 0xffff0000, v28
	v_pk_fma_f32 v[118:119], v[146:147], v[148:149], v[118:119]
	v_lshlrev_b32_e32 v146, 16, v81
	v_and_b32_e32 v147, 0xffff0000, v81
	v_pk_fma_f32 v[96:97], v[152:153], v[146:147], v[96:97]
	v_lshlrev_b32_e32 v146, 16, v76
	v_and_b32_e32 v147, 0xffff0000, v76
	v_pk_fma_f32 v[98:99], v[150:151], v[146:147], v[98:99]
	v_lshlrev_b32_e32 v146, 16, v33
	v_and_b32_e32 v147, 0xffff0000, v33
	v_pk_fma_f32 v[120:121], v[152:153], v[146:147], v[120:121]
	v_lshlrev_b32_e32 v146, 16, v32
	v_and_b32_e32 v147, 0xffff0000, v32
	v_pk_fma_f32 v[118:119], v[150:151], v[146:147], v[118:119]
	v_lshlrev_b32_e32 v146, 16, v21
	v_and_b32_e32 v147, 0xffff0000, v21
	s_waitcnt lgkmcnt(1)
	v_pk_fma_f32 v[146:147], v[160:161], v[146:147], v[96:97]
	v_lshlrev_b32_e32 v96, 16, v20
	v_and_b32_e32 v97, 0xffff0000, v20
	v_pk_fma_f32 v[148:149], v[158:159], v[96:97], v[98:99]
	v_lshlrev_b32_e32 v96, 16, v37
	v_and_b32_e32 v97, 0xffff0000, v37
	v_pk_fma_f32 v[120:121], v[160:161], v[96:97], v[120:121]
	v_lshlrev_b32_e32 v96, 16, v36
	v_and_b32_e32 v97, 0xffff0000, v36
	v_pk_fma_f32 v[118:119], v[158:159], v[96:97], v[118:119]
	v_mul_f32_e32 v96, 0x3fb8aa3b, v125
	v_exp_f32_e32 v104, v96
	s_nop 0
	v_pk_mul_f32 v[96:97], v[104:105], v[108:109] op_sel_hi:[0,1]
	v_pk_mul_f32 v[98:99], v[104:105], v[110:111] op_sel_hi:[0,1]
	v_cvt_pk_bf16_f32 v96, v96, v97
	v_cvt_pk_bf16_f32 v97, v98, v99
	v_pk_mul_f32 v[98:99], v[104:105], v[106:107] op_sel_hi:[0,1]
	v_cvt_pk_bf16_f32 v98, v98, v99
	v_pk_mul_f32 v[102:103], v[104:105], v[102:103] op_sel_hi:[0,1]
	v_mul_f32_e32 v99, 0xbfb8aa3b, v122
	v_mul_f32_e32 v104, 0xbfb8aa3b, v123
	v_exp_f32_e32 v99, v99
	v_exp_f32_e32 v104, v104
	v_add_f32_e32 v99, 1.0, v99
	v_add_f32_e32 v104, 1.0, v104
	v_rcp_f32_e32 v106, v99
	v_rcp_f32_e32 v107, v104
	v_mul_f32_e32 v99, 0xbfb8aa3b, v126
	v_mul_f32_e32 v104, 0xbfb8aa3b, v127
	v_exp_f32_e32 v99, v99
	v_exp_f32_e32 v104, v104
	v_pk_mul_f32 v[106:107], v[122:123], v[106:107]
	v_add_f32_e32 v99, 1.0, v99
	v_add_f32_e32 v104, 1.0, v104
	v_rcp_f32_e32 v108, v99
	v_rcp_f32_e32 v109, v104
	v_mul_f32_e32 v99, 0xbfb8aa3b, v146
	v_mul_f32_e32 v104, 0xbfb8aa3b, v147
	v_exp_f32_e32 v99, v99
	v_exp_f32_e32 v104, v104
	v_pk_mul_f32 v[108:109], v[126:127], v[108:109]
	v_add_f32_e32 v99, 1.0, v99
	v_add_f32_e32 v104, 1.0, v104
	v_rcp_f32_e32 v110, v99
	v_rcp_f32_e32 v111, v104
	v_mul_f32_e32 v99, 0xbfb8aa3b, v148
	v_mul_f32_e32 v104, 0xbfb8aa3b, v149
	v_exp_f32_e32 v99, v99
	v_exp_f32_e32 v104, v104
	v_pk_mul_f32 v[110:111], v[146:147], v[110:111]
	v_add_f32_e32 v99, 1.0, v99
	v_add_f32_e32 v104, 1.0, v104
	v_rcp_f32_e32 v122, v99
	v_rcp_f32_e32 v123, v104
	v_mul_f32_e32 v99, 0xbfb8aa3b, v154
	v_mul_f32_e32 v104, 0xbfb8aa3b, v155
	v_exp_f32_e32 v99, v99
	v_exp_f32_e32 v104, v104
	v_pk_mul_f32 v[122:123], v[148:149], v[122:123]
	v_add_f32_e32 v99, 1.0, v99
	v_add_f32_e32 v104, 1.0, v104
	v_rcp_f32_e32 v126, v99
	v_rcp_f32_e32 v127, v104
	v_mul_f32_e32 v99, 0xbfb8aa3b, v162
	v_mul_f32_e32 v104, 0xbfb8aa3b, v163
	v_exp_f32_e32 v99, v99
	v_exp_f32_e32 v104, v104
	v_pk_mul_f32 v[126:127], v[154:155], v[126:127]
	v_add_f32_e32 v99, 1.0, v99
	v_add_f32_e32 v104, 1.0, v104
	v_rcp_f32_e32 v146, v99
	v_rcp_f32_e32 v147, v104
	v_mul_f32_e32 v99, 0xbfb8aa3b, v120
	v_mul_f32_e32 v104, 0xbfb8aa3b, v121
	v_exp_f32_e32 v99, v99
	v_exp_f32_e32 v104, v104
	v_pk_mul_f32 v[146:147], v[162:163], v[146:147]
	v_add_f32_e32 v99, 1.0, v99
	v_add_f32_e32 v104, 1.0, v104
	v_rcp_f32_e32 v148, v99
	v_rcp_f32_e32 v149, v104
	v_mul_f32_e32 v99, 0xbfb8aa3b, v118
	v_mul_f32_e32 v104, 0xbfb8aa3b, v119
	v_exp_f32_e32 v99, v99
	v_exp_f32_e32 v104, v104
	v_pk_mul_f32 v[120:121], v[120:121], v[148:149]
	v_add_f32_e32 v99, 1.0, v99
	v_add_f32_e32 v104, 1.0, v104
	v_rcp_f32_e32 v148, v99
	v_rcp_f32_e32 v149, v104
	v_cvt_pk_bf16_f32 v99, v102, v103
	v_pk_mul_f32 v[118:119], v[118:119], v[148:149]
	v_pk_mul_f32 v[148:149], v[122:123], v[122:123]
	v_pk_mul_f32 v[150:151], v[118:119], v[118:119]
	v_mov_b32_e32 v153, v148
	v_mov_b32_e32 v152, v150
	v_mov_b32_e32 v148, v151
	v_pk_add_f32 v[148:149], v[152:153], v[148:149]
	v_pk_mul_f32 v[150:151], v[110:111], v[110:111]
	v_pk_mul_f32 v[152:153], v[120:121], v[120:121]
	v_mov_b32_e32 v155, v150
	v_mov_b32_e32 v154, v152
	v_pk_add_f32 v[148:149], v[148:149], v[154:155]
	v_mov_b32_e32 v150, v153
	v_pk_add_f32 v[148:149], v[148:149], v[150:151]
	v_pk_mul_f32 v[150:151], v[108:109], v[108:109]
	v_pk_mul_f32 v[152:153], v[146:147], v[146:147]
	v_mov_b32_e32 v155, v150
	v_mov_b32_e32 v154, v152
	v_pk_add_f32 v[148:149], v[148:149], v[154:155]
	v_mov_b32_e32 v150, v153
	v_pk_add_f32 v[148:149], v[148:149], v[150:151]
	v_pk_mul_f32 v[150:151], v[106:107], v[106:107]
	v_pk_mul_f32 v[152:153], v[126:127], v[126:127]
	v_mov_b32_e32 v155, v150
	v_mov_b32_e32 v154, v152
	v_pk_add_f32 v[148:149], v[148:149], v[154:155]
	v_mov_b32_e32 v150, v153
	v_pk_add_f32 v[148:149], v[148:149], v[150:151]
	ds_bpermute_b32 v151, v101, v149
	ds_bpermute_b32 v150, v101, v148
	v_ashrrev_i32_e32 v101, 31, v100
	v_lshl_add_u64 v[100:101], v[100:101], 4, s[4:5]
	global_store_dwordx4 v[100:101], v[96:99], off
	v_lshlrev_b32_e32 v152, 16, v87
	s_waitcnt lgkmcnt(0)
	v_pk_add_f32 v[148:149], v[148:149], v[150:151]
	ds_bpermute_b32 v151, v113, v149
	ds_bpermute_b32 v150, v113, v148
	ds_read_b32 v113, v130
	v_mul_f32_e32 v112, 0x3fb8aa3b, v112
	v_exp_f32_e32 v112, v112
	v_and_b32_e32 v153, 0xffff0000, v87
	s_waitcnt lgkmcnt(1)
	v_pk_add_f32 v[148:149], v[148:149], v[150:151]
	ds_bpermute_b32 v151, v115, v149
	ds_bpermute_b32 v150, v115, v148
	s_waitcnt lgkmcnt(2)
	v_mul_f32_e32 v100, v113, v112
	s_waitcnt lgkmcnt(0)
	v_pk_add_f32 v[102:103], v[148:149], v[150:151]
	ds_bpermute_b32 v105, v116, v103
	ds_bpermute_b32 v104, v116, v102
	s_nop 0
	v_lshlrev_b32_e32 v148, 16, v44
	v_and_b32_e32 v149, 0xffff0000, v44
	v_lshlrev_b32_e32 v150, 16, v85
	v_and_b32_e32 v151, 0xffff0000, v85
	s_waitcnt lgkmcnt(0)
	v_pk_add_f32 v[102:103], v[102:103], v[104:105]
	s_nop 0
	v_pk_add_f32 v[102:103], v[102:103], s[22:23] op_sel_hi:[1,0]
	s_nop 0
	v_mul_f32_e32 v104, 0x4b800000, v103
	v_cmp_gt_f32_e32 vcc, s36, v103
	s_nop 1
	v_cndmask_b32_e32 v103, v103, v104, vcc
	v_rsq_f32_e32 v103, v103
	s_nop 0
	v_mul_f32_e32 v96, 0x45800000, v103
	v_cndmask_b32_e32 v96, v103, v96, vcc
	v_pk_mul_f32 v[104:105], v[122:123], v[96:97] op_sel_hi:[1,0]
	v_pk_mul_f32 v[110:111], v[110:111], v[96:97] op_sel_hi:[1,0]
	v_pk_mul_f32 v[108:109], v[108:109], v[96:97] op_sel_hi:[1,0]
	v_pk_mul_f32 v[106:107], v[106:107], v[96:97] op_sel_hi:[1,0]
	v_cvt_pk_bf16_f32 v96, v104, v105
	v_cvt_pk_bf16_f32 v97, v110, v111
	v_cvt_pk_bf16_f32 v98, v108, v109
	v_cvt_pk_bf16_f32 v99, v106, v107
	ds_write_b128 v138, v[96:99] offset:17408
	v_pk_mul_f32 v[96:97], v[100:101], v[104:105] op_sel_hi:[0,1]
	v_pk_mul_f32 v[98:99], v[100:101], v[110:111] op_sel_hi:[0,1]
	v_cvt_pk_bf16_f32 v96, v96, v97
	v_cvt_pk_bf16_f32 v97, v98, v99
	v_pk_mul_f32 v[98:99], v[100:101], v[108:109] op_sel_hi:[0,1]
	v_pk_mul_f32 v[100:101], v[100:101], v[106:107] op_sel_hi:[0,1]
	v_cvt_pk_bf16_f32 v98, v98, v99
	v_cvt_pk_bf16_f32 v99, v100, v101
	ds_write_b128 v138, v[96:99] offset:52224
	ds_read_b32 v96, v114
	ds_read_b32 v108, v137
	v_mul_f32_e32 v97, 0x4b800000, v102
	v_cmp_gt_f32_e32 vcc, s36, v102
	s_waitcnt lgkmcnt(1)
	v_mul_f32_e32 v96, 0x3fb8aa3b, v96
	v_cndmask_b32_e32 v97, v102, v97, vcc
	v_rsq_f32_e32 v97, v97
	v_exp_f32_e32 v109, v96
	v_mul_f32_e32 v96, 0x45800000, v97
	v_cndmask_b32_e32 v96, v97, v96, vcc
	v_pk_mul_f32 v[100:101], v[118:119], v[96:97] op_sel_hi:[1,0]
	v_pk_mul_f32 v[102:103], v[120:121], v[96:97] op_sel_hi:[1,0]
	v_pk_mul_f32 v[104:105], v[146:147], v[96:97] op_sel_hi:[1,0]
	v_pk_mul_f32 v[106:107], v[126:127], v[96:97] op_sel_hi:[1,0]
	v_cvt_pk_bf16_f32 v96, v100, v101
	v_cvt_pk_bf16_f32 v97, v102, v103
	v_cvt_pk_bf16_f32 v98, v104, v105
	v_cvt_pk_bf16_f32 v99, v106, v107
	s_waitcnt lgkmcnt(0)
	v_mul_f32_e32 v108, v108, v109
	ds_write_b128 v136, v[96:99] offset:17408
	v_pk_mul_f32 v[96:97], v[108:109], v[100:101] op_sel_hi:[0,1]
	v_pk_mul_f32 v[98:99], v[108:109], v[102:103] op_sel_hi:[0,1]
	v_cvt_pk_bf16_f32 v96, v96, v97
	v_cvt_pk_bf16_f32 v97, v98, v99
	v_pk_mul_f32 v[98:99], v[108:109], v[104:105] op_sel_hi:[0,1]
	v_pk_mul_f32 v[100:101], v[108:109], v[106:107] op_sel_hi:[0,1]
	v_cvt_pk_bf16_f32 v98, v98, v99
	v_cvt_pk_bf16_f32 v99, v100, v101
	ds_write_b128 v136, v[96:99] offset:52224
	ds_read_b128 v[120:123], v124 offset:4096
	ds_read_b128 v[96:99], v124 offset:4112
	ds_read_b128 v[112:115], v124 offset:4608
	ds_read_b128 v[100:103], v124 offset:5120
	ds_read_b128 v[108:111], v124 offset:5632
	v_lshlrev_b32_e32 v104, 16, v78
	v_and_b32_e32 v105, 0xffff0000, v78
	s_waitcnt lgkmcnt(4)
	v_pk_fma_f32 v[116:117], v[120:121], v[104:105], 0 op_sel_hi:[1,1,0]
	v_lshlrev_b32_e32 v118, 16, v82
	v_and_b32_e32 v119, 0xffff0000, v82
	s_waitcnt lgkmcnt(2)
	v_pk_fma_f32 v[126:127], v[112:113], v[118:119], v[116:117]
	v_lshlrev_b32_e32 v146, 16, v86
	v_and_b32_e32 v147, 0xffff0000, v86
	s_waitcnt lgkmcnt(1)
	v_pk_fma_f32 v[146:147], v[100:101], v[146:147], v[126:127]
	v_pk_fma_f32 v[150:151], v[122:123], v[150:151], 0 op_sel_hi:[1,1,0]
	s_waitcnt lgkmcnt(0)
	v_pk_fma_f32 v[146:147], v[108:109], v[148:149], v[146:147]
	ds_read_b128 v[104:107], v124 offset:4624
	ds_read_b128 v[116:119], v124 offset:5136
	v_mul_f32_e32 v139, 0xbfb8aa3b, v147
	v_mul_f32_e32 v148, 0xbfb8aa3b, v146
	v_exp_f32_e32 v139, v139
	v_exp_f32_e32 v148, v148
	ds_read_b128 v[124:127], v124 offset:5648
	ds_read_b32 v130, v130
	v_add_f32_e32 v139, 1.0, v139
	v_add_f32_e32 v148, 1.0, v148
	v_rcp_f32_e32 v149, v139
	v_rcp_f32_e32 v148, v148
	v_pk_fma_f32 v[152:153], v[98:99], v[152:153], 0 op_sel_hi:[1,1,0]
	v_pk_mul_f32 v[146:147], v[146:147], v[148:149]
	v_lshlrev_b32_e32 v148, 16, v89
	v_and_b32_e32 v149, 0xffff0000, v89
	v_pk_fma_f32 v[148:149], v[114:115], v[148:149], v[150:151]
	v_lshlrev_b32_e32 v150, 16, v93
	v_and_b32_e32 v151, 0xffff0000, v93
	v_pk_fma_f32 v[148:149], v[102:103], v[150:151], v[148:149]
	v_lshlrev_b32_e32 v150, 16, v45
	v_and_b32_e32 v151, 0xffff0000, v45
	v_pk_fma_f32 v[148:149], v[110:111], v[150:151], v[148:149]
	s_waitcnt lgkmcnt(0)
	v_pk_mul_f32 v[146:147], v[130:131], v[146:147] op_sel_hi:[0,1]
	v_mul_f32_e32 v139, 0xbfb8aa3b, v149
	v_mul_f32_e32 v150, 0xbfb8aa3b, v148
	v_exp_f32_e32 v139, v139
	v_exp_f32_e32 v150, v150
	v_cvt_pk_bf16_f32 v146, v146, v147
	v_add_f32_e32 v139, 1.0, v139
	v_add_f32_e32 v150, 1.0, v150
	v_rcp_f32_e32 v151, v139
	v_rcp_f32_e32 v150, v150
	s_nop 0
	v_pk_mul_f32 v[148:149], v[148:149], v[150:151]
	s_nop 0
	v_pk_mul_f32 v[148:149], v[130:131], v[148:149] op_sel_hi:[0,1]
	v_lshlrev_b32_e32 v150, 16, v90
	v_and_b32_e32 v151, 0xffff0000, v90
	v_cvt_pk_bf16_f32 v147, v148, v149
	v_lshlrev_b32_e32 v148, 16, v92
	v_and_b32_e32 v149, 0xffff0000, v92
	v_pk_fma_f32 v[150:151], v[96:97], v[150:151], 0 op_sel_hi:[1,1,0]
	s_nop 0
	v_pk_fma_f32 v[148:149], v[104:105], v[148:149], v[150:151]
	v_lshlrev_b32_e32 v150, 16, v94
	v_and_b32_e32 v151, 0xffff0000, v94
	v_pk_fma_f32 v[148:149], v[116:117], v[150:151], v[148:149]
	v_lshlrev_b32_e32 v150, 16, v46
	v_and_b32_e32 v151, 0xffff0000, v46
	v_pk_fma_f32 v[148:149], v[124:125], v[150:151], v[148:149]
	s_nop 0
	v_mul_f32_e32 v139, 0xbfb8aa3b, v149
	v_mul_f32_e32 v150, 0xbfb8aa3b, v148
	v_exp_f32_e32 v139, v139
	v_exp_f32_e32 v150, v150
	v_add_f32_e32 v139, 1.0, v139
	v_add_f32_e32 v150, 1.0, v150
	v_rcp_f32_e32 v151, v139
	v_rcp_f32_e32 v150, v150
	s_nop 0
	v_pk_mul_f32 v[148:149], v[148:149], v[150:151]
	v_lshlrev_b32_e32 v150, 16, v91
	v_and_b32_e32 v151, 0xffff0000, v91
	v_pk_fma_f32 v[150:151], v[106:107], v[150:151], v[152:153]
	v_lshlrev_b32_e32 v152, 16, v95
	v_and_b32_e32 v153, 0xffff0000, v95
	v_pk_fma_f32 v[150:151], v[118:119], v[152:153], v[150:151]
	v_lshlrev_b32_e32 v152, 16, v47
	v_and_b32_e32 v153, 0xffff0000, v47
	v_pk_mul_f32 v[148:149], v[130:131], v[148:149] op_sel_hi:[0,1]
	v_pk_fma_f32 v[150:151], v[126:127], v[152:153], v[150:151]
	v_cvt_pk_bf16_f32 v148, v148, v149
	v_mul_f32_e32 v139, 0xbfb8aa3b, v151
	v_mul_f32_e32 v149, 0xbfb8aa3b, v150
	v_exp_f32_e32 v139, v139
	v_exp_f32_e32 v149, v149
	v_add_f32_e32 v139, 1.0, v139
	v_add_f32_e32 v149, 1.0, v149
	v_rcp_f32_e32 v153, v139
	v_rcp_f32_e32 v152, v149
	s_nop 0
	v_and_b32_e32 v139, 0xffff0000, v52
	v_pk_mul_f32 v[150:151], v[150:151], v[152:153]
	s_nop 0
	v_pk_mul_f32 v[150:151], v[130:131], v[150:151] op_sel_hi:[0,1]
	v_cvt_pk_bf16_f32 v149, v150, v151
	ds_write_b128 v138, v[146:149] offset:34816
	v_lshlrev_b32_e32 v138, 16, v52
	s_nop 0
	v_lshlrev_b32_e32 v146, 16, v58
	v_and_b32_e32 v147, 0xffff0000, v58
	v_pk_fma_f32 v[120:121], v[120:121], v[138:139], 0 op_sel_hi:[1,1,0]
	s_nop 0
	v_pk_fma_f32 v[112:113], v[112:113], v[146:147], v[120:121]
	s_nop 0
	v_lshlrev_b32_e32 v120, 16, v66
	v_and_b32_e32 v121, 0xffff0000, v66
	v_pk_fma_f32 v[100:101], v[100:101], v[120:121], v[112:113]
	s_nop 0
	v_lshlrev_b32_e32 v112, 16, v72
	v_and_b32_e32 v113, 0xffff0000, v72
	v_pk_fma_f32 v[100:101], v[108:109], v[112:113], v[100:101]
	v_lshlrev_b32_e32 v108, 16, v53
	v_mul_f32_e32 v112, 0xbfb8aa3b, v101
	v_exp_f32_e32 v120, v112
	v_mul_f32_e32 v112, 0xbfb8aa3b, v100
	v_exp_f32_e32 v121, v112
	v_and_b32_e32 v109, 0xffff0000, v53
	v_pk_fma_f32 v[108:109], v[122:123], v[108:109], 0 op_sel_hi:[1,1,0]
	v_lshlrev_b32_e32 v112, 16, v59
	v_and_b32_e32 v113, 0xffff0000, v59
	v_pk_fma_f32 v[108:109], v[114:115], v[112:113], v[108:109]
	v_add_f32_e32 v113, 1.0, v120
	v_rcp_f32_e32 v115, v113
	v_add_f32_e32 v113, 1.0, v121
	v_lshlrev_b32_e32 v120, 16, v67
	v_and_b32_e32 v121, 0xffff0000, v67
	v_lshlrev_b32_e32 v122, 16, v73
	v_and_b32_e32 v123, 0xffff0000, v73
	v_pk_fma_f32 v[102:103], v[102:103], v[120:121], v[108:109]
	v_rcp_f32_e32 v114, v113
	v_pk_fma_f32 v[102:103], v[110:111], v[122:123], v[102:103]
	ds_read_b32 v112, v137
	v_mul_f32_e32 v108, 0xbfb8aa3b, v103
	v_exp_f32_e32 v108, v108
	v_mul_f32_e32 v109, 0xbfb8aa3b, v102
	v_exp_f32_e32 v110, v109
	v_and_b32_e32 v111, 0xffff0000, v60
	v_add_f32_e32 v108, 1.0, v108
	v_rcp_f32_e32 v109, v108
	v_add_f32_e32 v108, 1.0, v110
	v_rcp_f32_e32 v108, v108
	v_lshlrev_b32_e32 v110, 16, v60
	v_pk_mul_f32 v[100:101], v[100:101], v[114:115]
	v_lshlrev_b32_e32 v114, 16, v68
	v_pk_mul_f32 v[102:103], v[102:103], v[108:109]
	v_lshlrev_b32_e32 v108, 16, v54
	v_and_b32_e32 v109, 0xffff0000, v54
	v_pk_fma_f32 v[96:97], v[96:97], v[108:109], 0 op_sel_hi:[1,1,0]
	v_and_b32_e32 v115, 0xffff0000, v68
	v_pk_fma_f32 v[96:97], v[104:105], v[110:111], v[96:97]
	v_lshlrev_b32_e32 v120, 16, v74
	v_and_b32_e32 v121, 0xffff0000, v74
	v_pk_fma_f32 v[96:97], v[116:117], v[114:115], v[96:97]
	s_waitcnt lgkmcnt(0)
	v_pk_mul_f32 v[100:101], v[100:101], v[112:113] op_sel_hi:[1,0]
	v_pk_fma_f32 v[96:97], v[124:125], v[120:121], v[96:97]
	v_cvt_pk_bf16_f32 v100, v100, v101
	v_mul_f32_e32 v101, 0xbfb8aa3b, v97
	v_exp_f32_e32 v104, v101
	v_mul_f32_e32 v101, 0xbfb8aa3b, v96
	v_exp_f32_e32 v105, v101
	v_pk_mul_f32 v[102:103], v[112:113], v[102:103] op_sel_hi:[0,1]
	v_cvt_pk_bf16_f32 v101, v102, v103
	v_add_f32_e32 v102, 1.0, v104
	v_rcp_f32_e32 v103, v102
	v_add_f32_e32 v102, 1.0, v105
	v_lshlrev_b32_e32 v104, 16, v55
	v_and_b32_e32 v105, 0xffff0000, v55
	v_lshlrev_b32_e32 v108, 16, v61
	v_and_b32_e32 v109, 0xffff0000, v61
	v_pk_fma_f32 v[98:99], v[98:99], v[104:105], 0 op_sel_hi:[1,1,0]
	v_lshlrev_b32_e32 v110, 16, v69
	v_and_b32_e32 v111, 0xffff0000, v69
	v_pk_fma_f32 v[98:99], v[106:107], v[108:109], v[98:99]
	v_lshlrev_b32_e32 v114, 16, v75
	v_and_b32_e32 v115, 0xffff0000, v75
	v_pk_fma_f32 v[98:99], v[118:119], v[110:111], v[98:99]
	v_rcp_f32_e32 v102, v102
	v_pk_fma_f32 v[98:99], v[126:127], v[114:115], v[98:99]
	v_lshlrev_b32_e32 v118, 4, v132
	v_mul_f32_e32 v104, 0xbfb8aa3b, v99
	v_exp_f32_e32 v104, v104
	v_mul_f32_e32 v105, 0xbfb8aa3b, v98
	v_exp_f32_e32 v106, v105
	v_pk_mul_f32 v[96:97], v[96:97], v[102:103]
	v_add_f32_e32 v104, 1.0, v104
	v_rcp_f32_e32 v105, v104
	v_add_f32_e32 v104, 1.0, v106
	v_rcp_f32_e32 v104, v104
	v_pk_mul_f32 v[96:97], v[112:113], v[96:97] op_sel_hi:[0,1]
	v_cvt_pk_bf16_f32 v102, v96, v97
	v_pk_mul_f32 v[96:97], v[98:99], v[104:105]
	s_nop 0
	v_pk_mul_f32 v[96:97], v[112:113], v[96:97] op_sel_hi:[0,1]
	v_cvt_pk_bf16_f32 v103, v96, v97
	ds_write_b128 v136, v[100:103] offset:34816
	s_cbranch_scc1 .LBB0_374
	s_lshr_b32 s20, s31, 8
	s_lshl_b32 s4, s31, 6
	s_and_b32 s30, s4, 0x7c0
	s_lshl_b64 s[6:7], s[20:21], 11
	s_or_b32 s4, s6, s30
	s_add_u32 s8, s4, -3
	s_addc_u32 s9, s7, 0x3ffff
	v_add_u32_e32 v8, s30, v134
	v_ashrrev_i32_e32 v135, 31, v134
	v_add_u32_e32 v11, s30, v128
	v_ashrrev_i32_e32 v129, 31, v128
	v_lshl_add_u64 v[0:1], s[8:9], 0, v[134:135]
	v_mov_b32_e32 v9, s4
	v_cmp_lt_i32_e64 s[4:5], 2, v8
	v_mov_b32_e32 v10, s7
	v_lshl_add_u64 v[4:5], s[8:9], 0, v[128:129]
	v_cmp_lt_i32_e64 s[6:7], 2, v11
	v_cndmask_b32_e64 v2, v9, v0, s[4:5]
	v_cndmask_b32_e64 v3, v10, v1, s[4:5]
	v_cndmask_b32_e64 v6, v9, v4, s[6:7]
	v_cndmask_b32_e64 v7, v10, v5, s[6:7]
	v_lshlrev_b64 v[6:7], 14, v[6:7]
	s_lshl_b32 s8, s31, 3
	v_lshlrev_b64 v[2:3], 14, v[2:3]
	v_lshl_add_u64 v[6:7], s[66:67], 0, v[6:7]
	s_and_b32 s20, s8, 0x700
	v_lshl_add_u64 v[2:3], s[66:67], 0, v[2:3]
	v_lshl_add_u64 v[6:7], v[6:7], 0, s[20:21]
	v_and_b32_e32 v130, 0xf0, v118
	v_lshl_add_u64 v[2:3], v[2:3], 0, s[20:21]
	v_lshl_add_u64 v[44:45], v[6:7], 0, v[130:131]
	v_lshl_add_u64 v[6:7], v[4:5], 0, 1
	v_cmp_lt_i32_e64 s[8:9], 1, v11
	v_lshl_add_u64 v[56:57], v[2:3], 0, v[130:131]
	v_lshl_add_u64 v[2:3], v[0:1], 0, 1
	v_cmp_lt_i32_e64 s[14:15], 1, v8
	v_cndmask_b32_e64 v6, v9, v6, s[8:9]
	v_cndmask_b32_e64 v7, v10, v7, s[8:9]
	v_cndmask_b32_e64 v2, v9, v2, s[14:15]
	v_cndmask_b32_e64 v3, v10, v3, s[14:15]
	v_lshlrev_b64 v[6:7], 14, v[6:7]
	v_lshlrev_b64 v[2:3], 14, v[2:3]
	v_lshl_add_u64 v[6:7], s[66:67], 0, v[6:7]
	v_lshl_add_u64 v[2:3], s[66:67], 0, v[2:3]
	v_lshl_add_u64 v[6:7], v[6:7], 0, s[20:21]
	v_lshl_add_u64 v[2:3], v[2:3], 0, s[20:21]
	v_lshl_add_u64 v[46:47], v[6:7], 0, v[130:131]
	v_lshl_add_u64 v[6:7], v[4:5], 0, 2
	v_cmp_lt_i32_e64 s[10:11], 0, v11
	v_lshl_add_u64 v[4:5], v[4:5], 0, 3
	v_cmp_lt_i32_e64 s[12:13], -1, v11
	v_lshl_add_u64 v[58:59], v[2:3], 0, v[130:131]
	v_lshl_add_u64 v[2:3], v[0:1], 0, 2
	v_cmp_lt_i32_e64 s[16:17], 0, v8
	v_lshl_add_u64 v[0:1], v[0:1], 0, 3
	v_cmp_lt_i32_e64 s[18:19], -1, v8
	v_cndmask_b32_e64 v6, v9, v6, s[10:11]
	v_cndmask_b32_e64 v7, v10, v7, s[10:11]
	v_cndmask_b32_e64 v4, v9, v4, s[12:13]
	v_cndmask_b32_e64 v5, v10, v5, s[12:13]
	v_cndmask_b32_e64 v2, v9, v2, s[16:17]
	v_cndmask_b32_e64 v3, v10, v3, s[16:17]
	v_cndmask_b32_e64 v0, v9, v0, s[18:19]
	v_cndmask_b32_e64 v1, v10, v1, s[18:19]
	v_lshlrev_b64 v[6:7], 14, v[6:7]
	v_lshlrev_b64 v[4:5], 14, v[4:5]
	v_lshlrev_b64 v[2:3], 14, v[2:3]
	v_lshlrev_b64 v[0:1], 14, v[0:1]
	v_lshl_add_u64 v[6:7], s[66:67], 0, v[6:7]
	v_lshl_add_u64 v[4:5], s[66:67], 0, v[4:5]
	v_lshl_add_u64 v[2:3], s[66:67], 0, v[2:3]
	v_lshl_add_u64 v[0:1], s[66:67], 0, v[0:1]
	v_lshl_add_u64 v[6:7], v[6:7], 0, s[20:21]
	v_lshl_add_u64 v[4:5], v[4:5], 0, s[20:21]
	v_lshl_add_u64 v[2:3], v[2:3], 0, s[20:21]
	v_lshl_add_u64 v[0:1], v[0:1], 0, s[20:21]
	v_lshl_add_u64 v[48:49], v[6:7], 0, v[130:131]
	v_lshl_add_u64 v[50:51], v[4:5], 0, v[130:131]
	v_lshl_add_u64 v[66:67], v[2:3], 0, v[130:131]
	v_lshl_add_u64 v[68:69], v[0:1], 0, v[130:131]
	global_load_dwordx4 v[40:43], v[44:45], off
	global_load_dwordx4 v[82:85], v[44:45], off offset:2048
	global_load_dwordx4 v[62:65], v[46:47], off
	global_load_dwordx4 v[76:79], v[46:47], off offset:2048
	global_load_dwordx4 v[180:183], v[48:49], off
	global_load_dwordx4 v[86:89], v[48:49], off offset:2048
	global_load_dwordx4 v[16:19], v[50:51], off
	global_load_dwordx4 v[20:23], v[50:51], off offset:2048
	global_load_dwordx4 v[0:3], v[56:57], off
	global_load_dwordx4 v[24:27], v[56:57], off offset:2048
	global_load_dwordx4 v[4:7], v[58:59], off
	global_load_dwordx4 v[28:31], v[58:59], off offset:2048
	global_load_dwordx4 v[8:11], v[66:67], off
	global_load_dwordx4 v[32:35], v[66:67], off offset:2048
	global_load_dwordx4 v[12:15], v[68:69], off
	global_load_dwordx4 v[36:39], v[68:69], off offset:2048
	v_add_co_u32_e32 v44, vcc, s37, v44
	v_mov_b32_e32 v129, 0
	s_nop 0
	v_addc_co_u32_e32 v45, vcc, 0, v45, vcc
	v_add_co_u32_e32 v46, vcc, s37, v46
	v_mov_b32_e32 v135, 0
	s_nop 0
	v_addc_co_u32_e32 v47, vcc, 0, v47, vcc
	global_load_dwordx4 v[92:95], v[44:45], off
	global_load_dwordx4 v[52:55], v[46:47], off
	v_add_co_u32_e32 v44, vcc, s37, v48
	s_nop 1
	v_addc_co_u32_e32 v45, vcc, 0, v49, vcc
	v_add_co_u32_e32 v46, vcc, s37, v50
	s_nop 1
	v_addc_co_u32_e32 v47, vcc, 0, v51, vcc
	v_add_co_u32_e32 v48, vcc, s37, v56
	global_load_dwordx4 v[176:179], v[44:45], off
	s_nop 0
	global_load_dwordx4 v[44:47], v[46:47], off
	v_addc_co_u32_e32 v49, vcc, 0, v57, vcc
	v_add_co_u32_e32 v50, vcc, s37, v58
	s_nop 1
	v_addc_co_u32_e32 v51, vcc, 0, v59, vcc
	global_load_dwordx4 v[172:175], v[48:49], off
	global_load_dwordx4 v[58:61], v[50:51], off
	v_add_co_u32_e32 v48, vcc, 0x1000, v66
	s_nop 1
	v_addc_co_u32_e32 v49, vcc, 0, v67, vcc
	v_add_co_u32_e32 v50, vcc, 0x1000, v68
	s_nop 1
	v_addc_co_u32_e32 v51, vcc, 0, v69, vcc
	global_load_dwordx4 v[66:69], v[48:49], off
	global_load_dwordx4 v[72:75], v[50:51], off
	s_and_saveexec_b64 s[34:35], s[2:3]
	s_cbranch_execz .LBB0_373
	s_lshr_b32 s20, s31, 5
	s_mov_b32 s31, s21
	s_lshl_b64 s[90:91], s[20:21], 11
	s_or_b64 s[30:31], s[90:91], s[30:31]
	v_lshl_add_u64 v[48:49], s[30:31], 0, v[132:133]
	v_lshlrev_b64 v[48:49], 2, v[48:49]
	v_lshl_add_u64 v[50:51], s[72:73], 0, v[48:49]
	v_lshl_add_u64 v[48:49], s[74:75], 0, v[48:49]
	global_load_dword v129, v[48:49], off
	global_load_dword v135, v[50:51], off
